# scan blocks signal completion; the block sharing their CU waits for it before taking queue work
# speedup vs baseline: 1.0425x; 1.0023x over previous
; DI int otid() { int t = __builtin_amdgcn_workitem_id_x(); asm volatile("" : "+v"(t)); return t; }
;   const int tid = otid();
;   const int NTASK = 64 + 1024 + 1024 + 128 + 288;
;   const int NEXTRA = (l == 0 && !dry) ? 456 : 0;
;   bool first = true;
;   for (;;) {
;     int id;
;     if (first && blockIdx.x < 64) {
;       id = blockIdx.x;
;     } else {
;       __syncthreads();
;       if (tid == 0) *(int*)(smem + SLOT) = 64 + (int)atomicAdd(&p.ctr[l + ci], 1u);
;       __syncthreads();
;       id = *(const int*)(smem + SLOT);
;     }
.LBB0_1221:
	s_or_b64 exec, exec, s[4:5]
	s_and_b64 s[4:5], s[50:51], exec
	s_movk_i32 s4, 0xba8
	s_cselect_b32 s92, s4, 0x9e0
	v_readlane_b32 s4, v254, 51
	v_mov_b32_e32 v4, v182
	s_lshl_b32 s6, s4, 8
	s_barrier
	v_readlane_b32 s98, v254, 0
	s_nop 0
	s_sub_u32 s99, s98, 0x100
	s_cmp_lt_u32 s99, 64
	s_cbranch_scc0 .Lpw_done
	s_load_dwordx2 s[100:101], s[0:1], 0x1b0
	s_lshl_b32 s99, s99, 2
	s_addk_i32 s99, 0x3000
	v_readlane_b32 s98, v254, 51
	s_waitcnt lgkmcnt(0)
	s_add_u32 s100, s100, s99
	s_addc_u32 s101, s101, 0
.Lpw_loop:
	s_sleep 32
	global_load_dword v5, v164, s[100:101] sc1
	s_waitcnt vmcnt(0)
	v_readfirstlane_b32 s99, v5
	s_nop 0
	s_cmp_le_u32 s99, s98
	s_cbranch_scc1 .Lpw_loop
.Lpw_done:
	v_readlane_b32 s5, v254, 52
	v_writelane_b32 v254, s6, 55
	s_load_dwordx2 s[6:7], s[0:1], 0x1b0
	s_mov_b32 s5, s45
	v_writelane_b32 v254, s4, 51
	v_cmp_eq_u32_e64 s[26:27], 0, v4
	s_nop 0
	v_writelane_b32 v254, s5, 52
	s_lshl_b64 s[4:5], s[4:5], 2
	s_waitcnt lgkmcnt(0)
	s_add_u32 s4, s6, s4
	s_addc_u32 s5, s7, s5
	v_writelane_b32 v254, s4, 57
	s_mov_b64 s[6:7], -1
	s_nop 0
	v_writelane_b32 v254, s5, 58
	v_writelane_b32 v254, s26, 59
	s_nop 1
	v_writelane_b32 v254, s27, 60
	s_branch .LBB0_1224

; DI void scan_task(const Params& p, int l, int isP, int b, int h, int rg, char* smem, const bool dry) {
;     ...
;   auto gload = [&](int c) {
;     const int tk = tokbase + c * 32;
;     rd0 = *(const float4*)(p.R + (size_t)(tk + ds) * RS + h * 64 + dj * 4);
;     rd1 = *(const float4*)(p.R + (size_t)(tk + 16 + ds) * RS + h * 64 + dj * 4);
;     const bf16_t* rb = (const bf16_t*)(p.R + (size_t)(tk + lst) * RS + 512) + h * 64 + lch * 8;
;     qr = *(const uint4*)(rb);
;     qk = *(const uint4*)(rb + 512);
;     qa = *(const uint4*)(rb + 1536);
;     qb = *(const uint4*)(rb + 2048);
;     if (tid < 64) {
;       const int s = tid >> 1, half = tid & 1;
;       rv = *(const uint4*)((const bf16_t*)(p.R + (size_t)(tk + s) * RS + 512) + 1024 + h * 64 + rg * 16 + half * 8);
;     }
;   };
;     ...
;   auto sstore = [&](int bi) {
;     char* bb = smem + bi * BUFB;
;     *(float4*)(bb + (ds * 64 + dj * 4) * 4) = rd0;
;     *(float4*)(bb + ((16 + ds) * 64 + dj * 4) * 4) = rd1;
;     {
;       CVT8(qa, alo, ahi)
;       float* d = (float*)(bb + 8192) + lst * 64 + lch * 8;
;       *(float4*)d = alo; *(float4*)(d + 4) = ahi;
;     }
;     {
;       CVT8(qb, blo, bhi)
;       float* d = (float*)(bb + 16384) + lst * 64 + lch * 8;
;       *(float4*)d = blo; *(float4*)(d + 4) = bhi;
;     }
;     *(uint4*)(bb + 24576 + (lst * 64 + lch * 8) * 2) = qr;
;     *(uint4*)(bb + 28672 + (lst * 64 + lch * 8) * 2) = qk;
;     if (tid < 64) {
;       const int s = tid >> 1, half = tid & 1;
;       CVT8(rv, vlo, vhi)
;       float* d = (float*)(bb + 32768) + s * 16 + half * 8;
;     ...
;   __syncthreads();
;   gload(0);
;   sstore(0);
;   __syncthreads();
;   for (int c = 0; c < nch; c++) {
;     const bool more = c + 1 < nch;
;     if (more) gload(c + 1);
;     const char* bb = smem + (c & 1) * BUFB;
;     const float* fw = (const float*)bb + jq * 4;
;     const float* fa = (const float*)(bb + 8192) + jq * 4;
;     const float* fb = (const float*)(bb + 16384) + jq * 4;
;     const char* pr = bb + 24576 + jq * 8;
;     const char* pk = bb + 28672 + jq * 8;
;     const float* vb = (const float*)(bb + 32768) + wave * 4 + g4;
;     float* yo = p.yscan + (size_t)(tokbase + c * 32 + jq) * 512 + h * 64 + i;
;     float ykeep0 = 0.f, ykeep1 = 0.f, yprev = 0.f;
;     f32x4 w4 = *(const f32x4*)fw, a4 = *(const f32x4*)fa, b4 = *(const f32x4*)fb;
;     uint2 ur = *(const uint2*)pr, uk = *(const uint2*)pk;
.Lscan_nostate:
	v_mov_b32_e32 v59, v69
	v_lshrrev_b32_e32 v66, 6, v182
	s_nop 0
	v_readfirstlane_b32 s28, v66
	s_setprio 3
	s_barrier
	global_load_dwordx4 v[84:87], v80, s[12:13]
	global_load_dwordx2 v[88:89], v81, s[12:13] offset:-1024
	global_load_dwordx2 v[90:91], v81, s[12:13]
	global_load_dwordx2 v[92:93], v81, s[12:13] offset:2048
	global_load_dwordx2 v[94:95], v81, s[12:13] offset:3072
	global_load_ushort v96, v82, s[12:13]
	s_add_u32 s12, s12, 0x1c000
	s_addc_u32 s13, s13, 0
	global_load_dwordx4 v[100:103], v80, s[12:13]
	global_load_dwordx2 v[104:105], v81, s[12:13] offset:-1024
	global_load_dwordx2 v[106:107], v81, s[12:13]
	global_load_dwordx2 v[108:109], v81, s[12:13] offset:2048
	global_load_dwordx2 v[98:99], v81, s[12:13] offset:3072
	global_load_ushort v97, v82, s[12:13]
	s_add_u32 s12, s12, 0x1c000
	s_addc_u32 s13, s13, 0
	s_waitcnt vmcnt(6)
	ds_write_b128 v78, v[84:87] offset:0
	v_lshlrev_b32_e32 v8, 16, v92
	v_and_b32_e32 v9, 0xffff0000, v92
	v_lshlrev_b32_e32 v10, 16, v93
	v_and_b32_e32 v11, 0xffff0000, v93
	ds_write_b128 v78, v[8:11] offset:4096
	v_lshlrev_b32_e32 v12, 16, v94
	v_and_b32_e32 v13, 0xffff0000, v94
	v_lshlrev_b32_e32 v14, 16, v95
	v_and_b32_e32 v15, 0xffff0000, v95
	ds_write_b128 v78, v[12:15] offset:8192
	v_lshlrev_b32_e32 v16, 16, v88
	v_and_b32_e32 v17, 0xffff0000, v88
	v_lshlrev_b32_e32 v18, 16, v89
	v_and_b32_e32 v19, 0xffff0000, v89
	ds_write_b128 v78, v[16:19] offset:12288
	v_lshlrev_b32_e32 v20, 16, v90
	v_and_b32_e32 v21, 0xffff0000, v90
	v_lshlrev_b32_e32 v22, 16, v91
	v_and_b32_e32 v23, 0xffff0000, v91
	ds_write_b128 v78, v[20:23] offset:16384
	v_lshlrev_b32_e32 v24, 16, v96
	ds_write_b32 v79, v24 offset:20480
	s_waitcnt lgkmcnt(0)
	s_barrier
	s_cmp_eq_u32 s28, 0
	s_cbranch_scc1 .Lstgs
	s_nop 5
	s_cmp_eq_u32 s28, 1
	s_cbranch_scc1 .Lstgs
	s_nop 5
	s_cmp_eq_u32 s28, 2
	s_cbranch_scc1 .Lstgs
	s_nop 5
.Lstgs:
	ds_read_b128 v[12:15], v76 offset:4096
	ds_read_b128 v[24:27], v76 offset:16384
	ds_read_b128 v[48:51], v77 offset:20480
	ds_read_b128 v[8:11], v76 offset:0
	ds_read_b128 v[16:19], v76 offset:8192
	ds_read_b128 v[20:23], v76 offset:12288
	ds_read_b128 v[32:35], v76 offset:4352
	ds_read_b128 v[44:47], v76 offset:16640
	ds_read_b128 v[28:31], v76 offset:256
	ds_read_b128 v[36:39], v76 offset:8448
	ds_read_b128 v[40:43], v76 offset:12544
	s_mov_b32 s16, 0

; DI void scan_task(const Params& p, int l, int isP, int b, int h, int rg, char* smem, const bool dry) {
;     ...
;   auto sstore = [&](int bi) {
;     char* bb = smem + bi * BUFB;
;     *(float4*)(bb + (ds * 64 + dj * 4) * 4) = rd0;
;     *(float4*)(bb + ((16 + ds) * 64 + dj * 4) * 4) = rd1;
;     {
;       CVT8(qa, alo, ahi)
;       float* d = (float*)(bb + 8192) + lst * 64 + lch * 8;
;       *(float4*)d = alo; *(float4*)(d + 4) = ahi;
;     }
;     {
;       CVT8(qb, blo, bhi)
;       float* d = (float*)(bb + 16384) + lst * 64 + lch * 8;
;       *(float4*)d = blo; *(float4*)(d + 4) = bhi;
;     }
;     *(uint4*)(bb + 24576 + (lst * 64 + lch * 8) * 2) = qr;
;     *(uint4*)(bb + 28672 + (lst * 64 + lch * 8) * 2) = qk;
;     if (tid < 64) {
;       const int s = tid >> 1, half = tid & 1;
;       CVT8(rv, vlo, vhi)
;       float* d = (float*)(bb + 32768) + s * 16 + half * 8;
;       *(float4*)d = vlo; *(float4*)(d + 4) = vhi;
;     }
;   };
;     ...
;     {
;       const float yl = rowsum16(yprev);
;       ykeep1 = (jq == 15) ? yl : ykeep1;
;     }
;     if (!dry) { yo[0] = ykeep0; yo[(size_t)16 * 512] = ykeep1; }
;     if (more) sstore((c + 1) & 1);
;     __syncthreads();
.Lscan_wdA:
	ds_write_b128 v78, v[100:103] offset:21504
	v_lshlrev_b32_e32 v8, 16, v108
	v_and_b32_e32 v9, 0xffff0000, v108
	v_lshlrev_b32_e32 v10, 16, v109
	v_and_b32_e32 v11, 0xffff0000, v109
	ds_write_b128 v78, v[8:11] offset:25600
	v_lshlrev_b32_e32 v12, 16, v98
	v_and_b32_e32 v13, 0xffff0000, v98
	v_lshlrev_b32_e32 v14, 16, v99
	v_and_b32_e32 v15, 0xffff0000, v99
	ds_write_b128 v78, v[12:15] offset:29696
	v_lshlrev_b32_e32 v16, 16, v104
	v_and_b32_e32 v17, 0xffff0000, v104
	v_lshlrev_b32_e32 v18, 16, v105
	v_and_b32_e32 v19, 0xffff0000, v105
	ds_write_b128 v78, v[16:19] offset:33792
	v_lshlrev_b32_e32 v20, 16, v106
	v_and_b32_e32 v21, 0xffff0000, v106
	v_lshlrev_b32_e32 v22, 16, v107
	v_and_b32_e32 v23, 0xffff0000, v107
	ds_write_b128 v78, v[20:23] offset:37888
	v_lshlrev_b32_e32 v24, 16, v97
	ds_write_b32 v79, v24 offset:41984
	s_waitcnt lgkmcnt(0)
	s_barrier
	s_cmp_eq_u32 s28, 0
	s_cbranch_scc1 .LstgbA
	s_nop 5
	s_cmp_eq_u32 s28, 1
	s_cbranch_scc1 .LstgbA
	s_nop 5
	s_cmp_eq_u32 s28, 2
	s_cbranch_scc1 .LstgbA
	s_nop 5
.LstgbA:
	ds_read_b128 v[12:15], v76 offset:25600
	ds_read_b128 v[24:27], v76 offset:37888
	ds_read_b128 v[48:51], v77 offset:41984
	ds_read_b128 v[8:11], v76 offset:21504
	ds_read_b128 v[16:19], v76 offset:29696
	ds_read_b128 v[20:23], v76 offset:33792
	ds_read_b128 v[32:35], v76 offset:25856
	ds_read_b128 v[44:47], v76 offset:38144
	ds_read_b128 v[28:31], v76 offset:21760
	ds_read_b128 v[36:39], v76 offset:29952
	ds_read_b128 v[40:43], v76 offset:34048
	v_add_f32_dpp v75, v66, v66 row_mirror row_mask:0xf bank_mask:0x3
	v_add_f32_dpp v74, v74, v74 row_half_mirror row_mask:0xf bank_mask:0x5
	v_add_f32_dpp v68, v68, v68 quad_perm:[1,0,3,2] row_mask:0xf bank_mask:0xf
	v_add_f32_dpp v75, v67, v67 row_mirror row_mask:0xf bank_mask:0xc
	v_add_f32_dpp v70, v70, v70 quad_perm:[1,0,3,2] row_mask:0xf bank_mask:0xf
	v_add_f32_dpp v72, v72, v72 quad_perm:[1,0,3,2] row_mask:0xf bank_mask:0xf
	v_add_f32_dpp v74, v75, v75 row_half_mirror row_mask:0xf bank_mask:0xa
	v_add_f32_dpp v68, v68, v68 quad_perm:[2,3,0,1] row_mask:0xf bank_mask:0xf
	v_add_f32_dpp v70, v70, v70 quad_perm:[2,3,0,1] row_mask:0xf bank_mask:0xf
	v_add_f32_dpp v74, v74, v74 quad_perm:[1,0,3,2] row_mask:0xf bank_mask:0xf
	v_add_f32_dpp v72, v72, v72 quad_perm:[2,3,0,1] row_mask:0xf bank_mask:0xf
	v_cndmask_b32_e64 v68, v68, v70, s[18:19]
	v_add_f32_dpp v74, v74, v74 quad_perm:[2,3,0,1] row_mask:0xf bank_mask:0xf
	v_cndmask_b32_e64 v72, v72, v74, s[18:19]
	v_cndmask_b32_e64 v68, v68, v72, s[20:21]
	global_store_dword v83, v68, s[14:15]
	s_add_u32 s14, s14, 0x8000
	s_addc_u32 s15, s15, 0

; DI void scan_task(const Params& p, int l, int isP, int b, int h, int rg, char* smem, const bool dry) {
;     ...
;     for (int s = 0; s < 32; s++) {
;       f32x4 w4n = w4, a4n = a4, b4n = b4;
;       uint2 urn = ur, ukn = uk;
;       float vn = v;
;       if (s < 31) {
;         w4n = *(const f32x4*)(fw + (s + 1) * 64);
;         a4n = *(const f32x4*)(fa + (s + 1) * 64);
;         b4n = *(const f32x4*)(fb + (s + 1) * 64);
;         urn = *(const uint2*)(pr + (s + 1) * 128);
;         ukn = *(const uint2*)(pk + (s + 1) * 128);
;         vn = vb[(s + 1) * 16];
;       }
;       __builtin_amdgcn_sched_barrier(0);
;       const f32x2 klo = {__uint_as_float(uk.x << 16), __uint_as_float(uk.x & 0xFFFF0000u)};
;       const f32x2 khi = {__uint_as_float(uk.y << 16), __uint_as_float(uk.y & 0xFFFF0000u)};
;       const f32x2 rlo = {__uint_as_float(ur.x << 16), __uint_as_float(ur.x & 0xFFFF0000u)};
;       const f32x2 rhi = {__uint_as_float(ur.y << 16), __uint_as_float(ur.y & 0xFFFF0000u)};
;       const f32x2 vv = {v, v};
;       const f32x2 t = Sa * a4.lo + Sb * a4.hi;
;       const f32x2 na = Sa * w4.lo + vv * klo;
;       const f32x2 nb = Sb * w4.hi + vv * khi;
;       float sa = t.x + t.y;
;       float yp = yprev;
;       rowsum16x2(sa, yp);
;       if (s >= 1 && s <= 16) ykeep0 = (jq == s - 1) ? yp : ykeep0;
;       if (s >= 17) ykeep1 = (jq == s - 17) ? yp : ykeep1;
;       const f32x2 sv = {sa, sa};
;       Sa = na + sv * b4.lo;
;       Sb = nb + sv * b4.hi;
;       const f32x2 yy = Sa * rlo + Sb * rhi;
;       yprev = yy.x + yy.y;
;       w4 = w4n; a4 = a4n; b4 = b4n; ur = urn; uk = ukn; v = vn;
;     }
.Lscan_noldB:
	s_waitcnt lgkmcnt(6)
	ds_read_b128 v[228:231], v76 offset:26112
	ds_read_b128 v[240:243], v76 offset:38400
	ds_read_b128 v[224:227], v76 offset:22016
	ds_read_b128 v[232:235], v76 offset:30208
	ds_read_b128 v[236:239], v76 offset:34304
	v_pk_mul_f32 v[56:57], v[4:5], v[12:13]
	v_pk_fma_f32 v[56:57], v[6:7], v[14:15], v[56:57]
	v_add_f32_e32 v58, v56, v57
	v_pk_mul_f32 v[60:61], v[48:49], v[24:25] op_sel_hi:[0,1]
	v_pk_mul_f32 v[62:63], v[48:49], v[26:27] op_sel_hi:[0,1]
	v_add_f32_dpp v58, v58, v58 quad_perm:[1,0,3,2] row_mask:0xf bank_mask:0xf bound_ctrl:1
	v_pk_fma_f32 v[60:61], v[4:5], v[8:9], v[60:61]
	v_pk_fma_f32 v[62:63], v[6:7], v[10:11], v[62:63]
	v_add_f32_dpp v58, v58, v58 quad_perm:[2,3,0,1] row_mask:0xf bank_mask:0xf bound_ctrl:1
	s_nop 1
	v_add_f32_dpp v58, v58, v58 row_half_mirror row_mask:0xf bank_mask:0xf bound_ctrl:1
	s_nop 1
	v_add_f32_dpp v58, v58, v58 row_mirror row_mask:0xf bank_mask:0xf bound_ctrl:1
	v_pk_fma_f32 v[4:5], v[58:59], v[16:17], v[60:61] op_sel_hi:[0,1,1]
	v_pk_fma_f32 v[6:7], v[58:59], v[18:19], v[62:63] op_sel_hi:[0,1,1]
	s_waitcnt lgkmcnt(6)
	ds_read_b128 v[12:15], v76 offset:26368
	ds_read_b128 v[24:27], v76 offset:38656
	ds_read_b128 v[8:11], v76 offset:22272
	ds_read_b128 v[16:19], v76 offset:30464
	ds_read_b128 v[52:55], v77 offset:42000
	v_pk_mul_f32 v[56:57], v[4:5], v[32:33]
	v_pk_mul_f32 v[64:65], v[4:5], v[20:21]
	v_pk_fma_f32 v[56:57], v[6:7], v[34:35], v[56:57]
	v_pk_fma_f32 v[64:65], v[6:7], v[22:23], v[64:65]
	v_add_f32_e32 v58, v56, v57
	v_pk_mul_f32 v[60:61], v[48:49], v[44:45] op_sel:[1,0] op_sel_hi:[1,1]
	v_pk_mul_f32 v[62:63], v[48:49], v[46:47] op_sel:[1,0] op_sel_hi:[1,1]
	v_add_f32_dpp v58, v58, v58 quad_perm:[1,0,3,2] row_mask:0xf bank_mask:0xf bound_ctrl:1
	v_pk_fma_f32 v[60:61], v[4:5], v[28:29], v[60:61]
	v_add_f32_e32 v66, v64, v65
	v_add_f32_dpp v58, v58, v58 quad_perm:[2,3,0,1] row_mask:0xf bank_mask:0xf bound_ctrl:1
	v_pk_fma_f32 v[62:63], v[6:7], v[30:31], v[62:63]
	s_nop 0
	v_add_f32_dpp v58, v58, v58 row_half_mirror row_mask:0xf bank_mask:0xf bound_ctrl:1
	ds_read_b128 v[20:23], v76 offset:34560
	s_nop 0
	v_add_f32_dpp v58, v58, v58 row_mirror row_mask:0xf bank_mask:0xf bound_ctrl:1
	v_pk_fma_f32 v[4:5], v[58:59], v[36:37], v[60:61] op_sel_hi:[0,1,1]
	v_pk_fma_f32 v[6:7], v[58:59], v[38:39], v[62:63] op_sel_hi:[0,1,1]
	s_waitcnt lgkmcnt(7)
	ds_read_b128 v[32:35], v76 offset:26624
	ds_read_b128 v[44:47], v76 offset:38912
	ds_read_b128 v[28:31], v76 offset:22528
	ds_read_b128 v[36:39], v76 offset:30720
	v_pk_mul_f32 v[56:57], v[4:5], v[228:229]
	v_pk_mul_f32 v[64:65], v[4:5], v[40:41]
	v_pk_fma_f32 v[56:57], v[6:7], v[230:231], v[56:57]
	v_pk_fma_f32 v[64:65], v[6:7], v[42:43], v[64:65]
	v_add_f32_e32 v58, v56, v57
	v_pk_mul_f32 v[60:61], v[50:51], v[240:241] op_sel_hi:[0,1]
	v_pk_mul_f32 v[62:63], v[50:51], v[242:243] op_sel_hi:[0,1]
	v_add_f32_dpp v58, v58, v58 quad_perm:[1,0,3,2] row_mask:0xf bank_mask:0xf bound_ctrl:1
	v_pk_fma_f32 v[60:61], v[4:5], v[224:225], v[60:61]
	v_add_f32_e32 v67, v64, v65
	v_add_f32_dpp v58, v58, v58 quad_perm:[2,3,0,1] row_mask:0xf bank_mask:0xf bound_ctrl:1
	v_pk_fma_f32 v[62:63], v[6:7], v[226:227], v[62:63]
	v_add_f32_dpp v68, v66, v66 row_mirror row_mask:0xf bank_mask:0x3
	v_add_f32_dpp v58, v58, v58 row_half_mirror row_mask:0xf bank_mask:0xf bound_ctrl:1
	s_nop 0
	v_add_f32_dpp v68, v67, v67 row_mirror row_mask:0xf bank_mask:0xc
	ds_read_b128 v[40:43], v76 offset:34816
	v_add_f32_dpp v58, v58, v58 row_mirror row_mask:0xf bank_mask:0xf bound_ctrl:1
	v_pk_fma_f32 v[4:5], v[58:59], v[232:233], v[60:61] op_sel_hi:[0,1,1]
	v_pk_fma_f32 v[6:7], v[58:59], v[234:235], v[62:63] op_sel_hi:[0,1,1]
	s_waitcnt lgkmcnt(7)
	ds_read_b128 v[228:231], v76 offset:26880
	ds_read_b128 v[240:243], v76 offset:39168
	ds_read_b128 v[224:227], v76 offset:22784
	ds_read_b128 v[232:235], v76 offset:30976
	v_pk_mul_f32 v[56:57], v[4:5], v[12:13]
	v_pk_mul_f32 v[64:65], v[4:5], v[236:237]
	v_pk_fma_f32 v[56:57], v[6:7], v[14:15], v[56:57]
	v_pk_fma_f32 v[64:65], v[6:7], v[238:239], v[64:65]
	v_add_f32_e32 v58, v56, v57
	v_pk_mul_f32 v[60:61], v[50:51], v[24:25] op_sel:[1,0] op_sel_hi:[1,1]
	v_pk_mul_f32 v[62:63], v[50:51], v[26:27] op_sel:[1,0] op_sel_hi:[1,1]
	v_add_f32_dpp v58, v58, v58 quad_perm:[1,0,3,2] row_mask:0xf bank_mask:0xf bound_ctrl:1
	v_pk_fma_f32 v[60:61], v[4:5], v[8:9], v[60:61]
	v_add_f32_e32 v66, v64, v65
	v_add_f32_dpp v58, v58, v58 quad_perm:[2,3,0,1] row_mask:0xf bank_mask:0xf bound_ctrl:1
	v_pk_fma_f32 v[62:63], v[6:7], v[10:11], v[62:63]
	s_nop 0
	v_add_f32_dpp v58, v58, v58 row_half_mirror row_mask:0xf bank_mask:0xf bound_ctrl:1
	ds_read_b128 v[236:239], v76 offset:35072
	s_nop 0
	v_add_f32_dpp v58, v58, v58 row_mirror row_mask:0xf bank_mask:0xf bound_ctrl:1
	v_pk_fma_f32 v[4:5], v[58:59], v[16:17], v[60:61] op_sel_hi:[0,1,1]
	v_pk_fma_f32 v[6:7], v[58:59], v[18:19], v[62:63] op_sel_hi:[0,1,1]
	s_waitcnt lgkmcnt(6)
	ds_read_b128 v[12:15], v76 offset:27136
	ds_read_b128 v[24:27], v76 offset:39424
	ds_read_b128 v[8:11], v76 offset:23040
	ds_read_b128 v[16:19], v76 offset:31232
	v_pk_mul_f32 v[56:57], v[4:5], v[32:33]
	v_pk_mul_f32 v[64:65], v[4:5], v[20:21]
	v_pk_fma_f32 v[56:57], v[6:7], v[34:35], v[56:57]
	v_pk_fma_f32 v[64:65], v[6:7], v[22:23], v[64:65]
	v_add_f32_e32 v58, v56, v57
	v_pk_mul_f32 v[60:61], v[52:53], v[44:45] op_sel_hi:[0,1]
	v_pk_mul_f32 v[62:63], v[52:53], v[46:47] op_sel_hi:[0,1]
	v_add_f32_dpp v58, v58, v58 quad_perm:[1,0,3,2] row_mask:0xf bank_mask:0xf bound_ctrl:1
	v_pk_fma_f32 v[60:61], v[4:5], v[28:29], v[60:61]
	v_add_f32_e32 v67, v64, v65
	v_add_f32_dpp v58, v58, v58 quad_perm:[2,3,0,1] row_mask:0xf bank_mask:0xf bound_ctrl:1
	v_pk_fma_f32 v[62:63], v[6:7], v[30:31], v[62:63]
	v_add_f32_dpp v69, v66, v66 row_mirror row_mask:0xf bank_mask:0x3
	v_add_f32_dpp v58, v58, v58 row_half_mirror row_mask:0xf bank_mask:0xf bound_ctrl:1
	s_nop 0
	v_add_f32_dpp v69, v67, v67 row_mirror row_mask:0xf bank_mask:0xc
	ds_read_b128 v[20:23], v76 offset:35328
	v_add_f32_dpp v58, v58, v58 row_mirror row_mask:0xf bank_mask:0xf bound_ctrl:1
	v_pk_fma_f32 v[4:5], v[58:59], v[36:37], v[60:61] op_sel_hi:[0,1,1]
	v_pk_fma_f32 v[6:7], v[58:59], v[38:39], v[62:63] op_sel_hi:[0,1,1]
	s_waitcnt lgkmcnt(6)
; DI void scan_task(const Params& p, int l, int isP, int b, int h, int rg, char* smem, const bool dry) {
;     ...
;     for (int s = 0; s < 32; s++) {
;       f32x4 w4n = w4, a4n = a4, b4n = b4;
;       uint2 urn = ur, ukn = uk;
;       float vn = v;
;       if (s < 31) {
;         w4n = *(const f32x4*)(fw + (s + 1) * 64);
;         a4n = *(const f32x4*)(fa + (s + 1) * 64);
;         b4n = *(const f32x4*)(fb + (s + 1) * 64);
;         urn = *(const uint2*)(pr + (s + 1) * 128);
;         ukn = *(const uint2*)(pk + (s + 1) * 128);
;         vn = vb[(s + 1) * 16];
;       }
;       __builtin_amdgcn_sched_barrier(0);
;       const f32x2 klo = {__uint_as_float(uk.x << 16), __uint_as_float(uk.x & 0xFFFF0000u)};
;       const f32x2 khi = {__uint_as_float(uk.y << 16), __uint_as_float(uk.y & 0xFFFF0000u)};
;       const f32x2 rlo = {__uint_as_float(ur.x << 16), __uint_as_float(ur.x & 0xFFFF0000u)};
;       const f32x2 rhi = {__uint_as_float(ur.y << 16), __uint_as_float(ur.y & 0xFFFF0000u)};
;       const f32x2 vv = {v, v};
;       const f32x2 t = Sa * a4.lo + Sb * a4.hi;
;       const f32x2 na = Sa * w4.lo + vv * klo;
;       const f32x2 nb = Sb * w4.hi + vv * khi;
;       float sa = t.x + t.y;
;       float yp = yprev;
;       rowsum16x2(sa, yp);
;       if (s >= 1 && s <= 16) ykeep0 = (jq == s - 1) ? yp : ykeep0;
;       if (s >= 17) ykeep1 = (jq == s - 17) ? yp : ykeep1;
;       const f32x2 sv = {sa, sa};
;       Sa = na + sv * b4.lo;
;       Sb = nb + sv * b4.hi;
;       const f32x2 yy = Sa * rlo + Sb * rhi;
;       yprev = yy.x + yy.y;
;       w4 = w4n; a4 = a4n; b4 = b4n; ur = urn; uk = ukn; v = vn;
;     }
	ds_read_b128 v[32:35], v76 offset:27392
	ds_read_b128 v[44:47], v76 offset:39680
	ds_read_b128 v[28:31], v76 offset:23296
	ds_read_b128 v[36:39], v76 offset:31488
	ds_read_b128 v[48:51], v77 offset:42016
	v_pk_mul_f32 v[56:57], v[4:5], v[228:229]
	v_pk_mul_f32 v[64:65], v[4:5], v[40:41]
	v_pk_fma_f32 v[56:57], v[6:7], v[230:231], v[56:57]
	v_pk_fma_f32 v[64:65], v[6:7], v[42:43], v[64:65]
	v_add_f32_e32 v58, v56, v57
	v_pk_mul_f32 v[60:61], v[52:53], v[240:241] op_sel:[1,0] op_sel_hi:[1,1]
	v_pk_mul_f32 v[62:63], v[52:53], v[242:243] op_sel:[1,0] op_sel_hi:[1,1]
	v_add_f32_dpp v58, v58, v58 quad_perm:[1,0,3,2] row_mask:0xf bank_mask:0xf bound_ctrl:1
	v_pk_fma_f32 v[60:61], v[4:5], v[224:225], v[60:61]
	v_add_f32_e32 v66, v64, v65
	v_add_f32_dpp v58, v58, v58 quad_perm:[2,3,0,1] row_mask:0xf bank_mask:0xf bound_ctrl:1
	v_pk_fma_f32 v[62:63], v[6:7], v[226:227], v[62:63]
	v_add_f32_dpp v68, v68, v68 row_half_mirror row_mask:0xf bank_mask:0x5
	v_add_f32_dpp v58, v58, v58 row_half_mirror row_mask:0xf bank_mask:0xf bound_ctrl:1
	s_nop 0
	v_add_f32_dpp v68, v69, v69 row_half_mirror row_mask:0xf bank_mask:0xa
	ds_read_b128 v[40:43], v76 offset:35584
	v_add_f32_dpp v58, v58, v58 row_mirror row_mask:0xf bank_mask:0xf bound_ctrl:1
	v_pk_fma_f32 v[4:5], v[58:59], v[232:233], v[60:61] op_sel_hi:[0,1,1]
	v_pk_fma_f32 v[6:7], v[58:59], v[234:235], v[62:63] op_sel_hi:[0,1,1]
	s_waitcnt lgkmcnt(7)
	ds_read_b128 v[228:231], v76 offset:27648
	ds_read_b128 v[240:243], v76 offset:39936
	ds_read_b128 v[224:227], v76 offset:23552
	ds_read_b128 v[232:235], v76 offset:31744
	v_pk_mul_f32 v[56:57], v[4:5], v[12:13]
	v_pk_mul_f32 v[64:65], v[4:5], v[236:237]
	v_pk_fma_f32 v[56:57], v[6:7], v[14:15], v[56:57]
	v_pk_fma_f32 v[64:65], v[6:7], v[238:239], v[64:65]
	v_add_f32_e32 v58, v56, v57
	v_pk_mul_f32 v[60:61], v[54:55], v[24:25] op_sel_hi:[0,1]
	v_pk_mul_f32 v[62:63], v[54:55], v[26:27] op_sel_hi:[0,1]
	v_add_f32_dpp v58, v58, v58 quad_perm:[1,0,3,2] row_mask:0xf bank_mask:0xf bound_ctrl:1
	v_pk_fma_f32 v[60:61], v[4:5], v[8:9], v[60:61]
	v_add_f32_e32 v67, v64, v65
	v_add_f32_dpp v58, v58, v58 quad_perm:[2,3,0,1] row_mask:0xf bank_mask:0xf bound_ctrl:1
	v_pk_fma_f32 v[62:63], v[6:7], v[10:11], v[62:63]
	v_add_f32_dpp v70, v66, v66 row_mirror row_mask:0xf bank_mask:0x3
	v_add_f32_dpp v58, v58, v58 row_half_mirror row_mask:0xf bank_mask:0xf bound_ctrl:1
	s_nop 0
	v_add_f32_dpp v70, v67, v67 row_mirror row_mask:0xf bank_mask:0xc
	ds_read_b128 v[236:239], v76 offset:35840
	v_add_f32_dpp v58, v58, v58 row_mirror row_mask:0xf bank_mask:0xf bound_ctrl:1
	v_pk_fma_f32 v[4:5], v[58:59], v[16:17], v[60:61] op_sel_hi:[0,1,1]
	v_pk_fma_f32 v[6:7], v[58:59], v[18:19], v[62:63] op_sel_hi:[0,1,1]
	s_waitcnt lgkmcnt(7)
	ds_read_b128 v[12:15], v76 offset:27904
	ds_read_b128 v[24:27], v76 offset:40192
	ds_read_b128 v[8:11], v76 offset:23808
	ds_read_b128 v[16:19], v76 offset:32000
	v_pk_mul_f32 v[56:57], v[4:5], v[32:33]
	v_pk_mul_f32 v[64:65], v[4:5], v[20:21]
	v_pk_fma_f32 v[56:57], v[6:7], v[34:35], v[56:57]
	v_pk_fma_f32 v[64:65], v[6:7], v[22:23], v[64:65]
	v_add_f32_e32 v58, v56, v57
	v_pk_mul_f32 v[60:61], v[54:55], v[44:45] op_sel:[1,0] op_sel_hi:[1,1]
	v_pk_mul_f32 v[62:63], v[54:55], v[46:47] op_sel:[1,0] op_sel_hi:[1,1]
	v_add_f32_dpp v58, v58, v58 quad_perm:[1,0,3,2] row_mask:0xf bank_mask:0xf bound_ctrl:1
	v_pk_fma_f32 v[60:61], v[4:5], v[28:29], v[60:61]
	v_add_f32_e32 v66, v64, v65
	v_add_f32_dpp v58, v58, v58 quad_perm:[2,3,0,1] row_mask:0xf bank_mask:0xf bound_ctrl:1
	v_pk_fma_f32 v[62:63], v[6:7], v[30:31], v[62:63]
	s_nop 0
	v_add_f32_dpp v58, v58, v58 row_half_mirror row_mask:0xf bank_mask:0xf bound_ctrl:1
	ds_read_b128 v[20:23], v76 offset:36096
	s_nop 0
	v_add_f32_dpp v58, v58, v58 row_mirror row_mask:0xf bank_mask:0xf bound_ctrl:1
	v_pk_fma_f32 v[4:5], v[58:59], v[36:37], v[60:61] op_sel_hi:[0,1,1]
	v_pk_fma_f32 v[6:7], v[58:59], v[38:39], v[62:63] op_sel_hi:[0,1,1]
	s_waitcnt lgkmcnt(6)
	ds_read_b128 v[32:35], v76 offset:28160
	ds_read_b128 v[44:47], v76 offset:40448
	ds_read_b128 v[28:31], v76 offset:24064
	ds_read_b128 v[36:39], v76 offset:32256
	v_pk_mul_f32 v[56:57], v[4:5], v[228:229]
	v_pk_mul_f32 v[64:65], v[4:5], v[40:41]
	v_pk_fma_f32 v[56:57], v[6:7], v[230:231], v[56:57]
	v_pk_fma_f32 v[64:65], v[6:7], v[42:43], v[64:65]
	v_add_f32_e32 v58, v56, v57
	v_pk_mul_f32 v[60:61], v[48:49], v[240:241] op_sel_hi:[0,1]
	v_pk_mul_f32 v[62:63], v[48:49], v[242:243] op_sel_hi:[0,1]
	v_add_f32_dpp v58, v58, v58 quad_perm:[1,0,3,2] row_mask:0xf bank_mask:0xf bound_ctrl:1
	v_pk_fma_f32 v[60:61], v[4:5], v[224:225], v[60:61]
	v_add_f32_e32 v67, v64, v65
	v_add_f32_dpp v58, v58, v58 quad_perm:[2,3,0,1] row_mask:0xf bank_mask:0xf bound_ctrl:1
	v_pk_fma_f32 v[62:63], v[6:7], v[226:227], v[62:63]
	v_add_f32_dpp v71, v66, v66 row_mirror row_mask:0xf bank_mask:0x3
	v_add_f32_dpp v58, v58, v58 row_half_mirror row_mask:0xf bank_mask:0xf bound_ctrl:1
	s_nop 0
	v_add_f32_dpp v71, v67, v67 row_mirror row_mask:0xf bank_mask:0xc
	ds_read_b128 v[40:43], v76 offset:36352
	v_add_f32_dpp v58, v58, v58 row_mirror row_mask:0xf bank_mask:0xf bound_ctrl:1
	v_pk_fma_f32 v[4:5], v[58:59], v[232:233], v[60:61] op_sel_hi:[0,1,1]
	v_pk_fma_f32 v[6:7], v[58:59], v[234:235], v[62:63] op_sel_hi:[0,1,1]
	s_waitcnt lgkmcnt(6)
; DI void scan_task(const Params& p, int l, int isP, int b, int h, int rg, char* smem, const bool dry) {
;     ...
;     for (int s = 0; s < 32; s++) {
;       f32x4 w4n = w4, a4n = a4, b4n = b4;
;       uint2 urn = ur, ukn = uk;
;       float vn = v;
;       if (s < 31) {
;         w4n = *(const f32x4*)(fw + (s + 1) * 64);
;         a4n = *(const f32x4*)(fa + (s + 1) * 64);
;         b4n = *(const f32x4*)(fb + (s + 1) * 64);
;         urn = *(const uint2*)(pr + (s + 1) * 128);
;         ukn = *(const uint2*)(pk + (s + 1) * 128);
;         vn = vb[(s + 1) * 16];
;       }
;       __builtin_amdgcn_sched_barrier(0);
;       const f32x2 klo = {__uint_as_float(uk.x << 16), __uint_as_float(uk.x & 0xFFFF0000u)};
;       const f32x2 khi = {__uint_as_float(uk.y << 16), __uint_as_float(uk.y & 0xFFFF0000u)};
;       const f32x2 rlo = {__uint_as_float(ur.x << 16), __uint_as_float(ur.x & 0xFFFF0000u)};
;       const f32x2 rhi = {__uint_as_float(ur.y << 16), __uint_as_float(ur.y & 0xFFFF0000u)};
;       const f32x2 vv = {v, v};
;       const f32x2 t = Sa * a4.lo + Sb * a4.hi;
;       const f32x2 na = Sa * w4.lo + vv * klo;
;       const f32x2 nb = Sb * w4.hi + vv * khi;
;       float sa = t.x + t.y;
;       float yp = yprev;
;       rowsum16x2(sa, yp);
;       if (s >= 1 && s <= 16) ykeep0 = (jq == s - 1) ? yp : ykeep0;
;       if (s >= 17) ykeep1 = (jq == s - 17) ? yp : ykeep1;
;       const f32x2 sv = {sa, sa};
;       Sa = na + sv * b4.lo;
;       Sb = nb + sv * b4.hi;
;       const f32x2 yy = Sa * rlo + Sb * rhi;
;       yprev = yy.x + yy.y;
;       w4 = w4n; a4 = a4n; b4 = b4n; ur = urn; uk = ukn; v = vn;
;     }
	ds_read_b128 v[228:231], v76 offset:28416
	ds_read_b128 v[240:243], v76 offset:40704
	ds_read_b128 v[224:227], v76 offset:24320
	ds_read_b128 v[232:235], v76 offset:32512
	ds_read_b128 v[52:55], v77 offset:42032
	v_pk_mul_f32 v[56:57], v[4:5], v[12:13]
	v_pk_mul_f32 v[64:65], v[4:5], v[236:237]
	v_pk_fma_f32 v[56:57], v[6:7], v[14:15], v[56:57]
	v_pk_fma_f32 v[64:65], v[6:7], v[238:239], v[64:65]
	v_add_f32_e32 v58, v56, v57
	v_pk_mul_f32 v[60:61], v[48:49], v[24:25] op_sel:[1,0] op_sel_hi:[1,1]
	v_pk_mul_f32 v[62:63], v[48:49], v[26:27] op_sel:[1,0] op_sel_hi:[1,1]
	v_add_f32_dpp v58, v58, v58 quad_perm:[1,0,3,2] row_mask:0xf bank_mask:0xf bound_ctrl:1
	v_pk_fma_f32 v[60:61], v[4:5], v[8:9], v[60:61]
	v_add_f32_e32 v66, v64, v65
	v_add_f32_dpp v58, v58, v58 quad_perm:[2,3,0,1] row_mask:0xf bank_mask:0xf bound_ctrl:1
	v_pk_fma_f32 v[62:63], v[6:7], v[10:11], v[62:63]
	v_add_f32_dpp v70, v70, v70 row_half_mirror row_mask:0xf bank_mask:0x5
	v_add_f32_dpp v58, v58, v58 row_half_mirror row_mask:0xf bank_mask:0xf bound_ctrl:1
	s_nop 0
	v_add_f32_dpp v70, v71, v71 row_half_mirror row_mask:0xf bank_mask:0xa
	ds_read_b128 v[236:239], v76 offset:36608
	v_add_f32_dpp v58, v58, v58 row_mirror row_mask:0xf bank_mask:0xf bound_ctrl:1
	v_pk_fma_f32 v[4:5], v[58:59], v[16:17], v[60:61] op_sel_hi:[0,1,1]
	v_pk_fma_f32 v[6:7], v[58:59], v[18:19], v[62:63] op_sel_hi:[0,1,1]
	s_waitcnt lgkmcnt(7)
	ds_read_b128 v[12:15], v76 offset:28672
	ds_read_b128 v[24:27], v76 offset:40960
	ds_read_b128 v[8:11], v76 offset:24576
	ds_read_b128 v[16:19], v76 offset:32768
	v_pk_mul_f32 v[56:57], v[4:5], v[32:33]
	v_pk_mul_f32 v[64:65], v[4:5], v[20:21]
	v_pk_fma_f32 v[56:57], v[6:7], v[34:35], v[56:57]
	v_pk_fma_f32 v[64:65], v[6:7], v[22:23], v[64:65]
	v_add_f32_e32 v58, v56, v57
	v_pk_mul_f32 v[60:61], v[50:51], v[44:45] op_sel_hi:[0,1]
	v_pk_mul_f32 v[62:63], v[50:51], v[46:47] op_sel_hi:[0,1]
	v_add_f32_dpp v58, v58, v58 quad_perm:[1,0,3,2] row_mask:0xf bank_mask:0xf bound_ctrl:1
	v_pk_fma_f32 v[60:61], v[4:5], v[28:29], v[60:61]
	v_add_f32_e32 v67, v64, v65
	v_add_f32_dpp v58, v58, v58 quad_perm:[2,3,0,1] row_mask:0xf bank_mask:0xf bound_ctrl:1
	v_pk_fma_f32 v[62:63], v[6:7], v[30:31], v[62:63]
	v_add_f32_dpp v72, v66, v66 row_mirror row_mask:0xf bank_mask:0x3
	v_add_f32_dpp v58, v58, v58 row_half_mirror row_mask:0xf bank_mask:0xf bound_ctrl:1
	s_nop 0
	v_add_f32_dpp v72, v67, v67 row_mirror row_mask:0xf bank_mask:0xc
	ds_read_b128 v[20:23], v76 offset:36864
	v_add_f32_dpp v58, v58, v58 row_mirror row_mask:0xf bank_mask:0xf bound_ctrl:1
	v_pk_fma_f32 v[4:5], v[58:59], v[36:37], v[60:61] op_sel_hi:[0,1,1]
	v_pk_fma_f32 v[6:7], v[58:59], v[38:39], v[62:63] op_sel_hi:[0,1,1]
	s_waitcnt lgkmcnt(7)
	ds_read_b128 v[32:35], v76 offset:28928
	ds_read_b128 v[44:47], v76 offset:41216
	ds_read_b128 v[28:31], v76 offset:24832
	ds_read_b128 v[36:39], v76 offset:33024
	v_pk_mul_f32 v[56:57], v[4:5], v[228:229]
	v_pk_mul_f32 v[64:65], v[4:5], v[40:41]
	v_pk_fma_f32 v[56:57], v[6:7], v[230:231], v[56:57]
	v_pk_fma_f32 v[64:65], v[6:7], v[42:43], v[64:65]
	v_add_f32_e32 v58, v56, v57
	v_pk_mul_f32 v[60:61], v[50:51], v[240:241] op_sel:[1,0] op_sel_hi:[1,1]
	v_pk_mul_f32 v[62:63], v[50:51], v[242:243] op_sel:[1,0] op_sel_hi:[1,1]
	v_add_f32_dpp v58, v58, v58 quad_perm:[1,0,3,2] row_mask:0xf bank_mask:0xf bound_ctrl:1
	v_pk_fma_f32 v[60:61], v[4:5], v[224:225], v[60:61]
	v_add_f32_e32 v66, v64, v65
	v_add_f32_dpp v58, v58, v58 quad_perm:[2,3,0,1] row_mask:0xf bank_mask:0xf bound_ctrl:1
	v_pk_fma_f32 v[62:63], v[6:7], v[226:227], v[62:63]
	s_nop 0
	v_add_f32_dpp v58, v58, v58 row_half_mirror row_mask:0xf bank_mask:0xf bound_ctrl:1
	ds_read_b128 v[40:43], v76 offset:37120
	s_nop 0
	v_add_f32_dpp v58, v58, v58 row_mirror row_mask:0xf bank_mask:0xf bound_ctrl:1
	v_pk_fma_f32 v[4:5], v[58:59], v[232:233], v[60:61] op_sel_hi:[0,1,1]
	v_pk_fma_f32 v[6:7], v[58:59], v[234:235], v[62:63] op_sel_hi:[0,1,1]
	s_waitcnt lgkmcnt(6)
	ds_read_b128 v[228:231], v76 offset:29184
	ds_read_b128 v[240:243], v76 offset:41472
	ds_read_b128 v[224:227], v76 offset:25088
	ds_read_b128 v[232:235], v76 offset:33280
	v_pk_mul_f32 v[56:57], v[4:5], v[12:13]
	v_pk_mul_f32 v[64:65], v[4:5], v[236:237]
	v_pk_fma_f32 v[56:57], v[6:7], v[14:15], v[56:57]
	v_pk_fma_f32 v[64:65], v[6:7], v[238:239], v[64:65]
	v_add_f32_e32 v58, v56, v57
	v_pk_mul_f32 v[60:61], v[52:53], v[24:25] op_sel_hi:[0,1]
	v_pk_mul_f32 v[62:63], v[52:53], v[26:27] op_sel_hi:[0,1]
	v_add_f32_dpp v58, v58, v58 quad_perm:[1,0,3,2] row_mask:0xf bank_mask:0xf bound_ctrl:1
	v_pk_fma_f32 v[60:61], v[4:5], v[8:9], v[60:61]
	v_add_f32_e32 v67, v64, v65
	v_add_f32_dpp v58, v58, v58 quad_perm:[2,3,0,1] row_mask:0xf bank_mask:0xf bound_ctrl:1
	v_pk_fma_f32 v[62:63], v[6:7], v[10:11], v[62:63]
	v_add_f32_dpp v73, v66, v66 row_mirror row_mask:0xf bank_mask:0x3
	v_add_f32_dpp v58, v58, v58 row_half_mirror row_mask:0xf bank_mask:0xf bound_ctrl:1
	s_nop 0
	v_add_f32_dpp v73, v67, v67 row_mirror row_mask:0xf bank_mask:0xc
	ds_read_b128 v[236:239], v76 offset:37376
	v_add_f32_dpp v58, v58, v58 row_mirror row_mask:0xf bank_mask:0xf bound_ctrl:1
	v_pk_fma_f32 v[4:5], v[58:59], v[16:17], v[60:61] op_sel_hi:[0,1,1]
	v_pk_fma_f32 v[6:7], v[58:59], v[18:19], v[62:63] op_sel_hi:[0,1,1]
	s_waitcnt lgkmcnt(6)
; DI void scan_task(const Params& p, int l, int isP, int b, int h, int rg, char* smem, const bool dry) {
;     ...
;   auto sstore = [&](int bi) {
;     char* bb = smem + bi * BUFB;
;     *(float4*)(bb + (ds * 64 + dj * 4) * 4) = rd0;
;     *(float4*)(bb + ((16 + ds) * 64 + dj * 4) * 4) = rd1;
;     {
;       CVT8(qa, alo, ahi)
;       float* d = (float*)(bb + 8192) + lst * 64 + lch * 8;
;       *(float4*)d = alo; *(float4*)(d + 4) = ahi;
;     }
;     {
;       CVT8(qb, blo, bhi)
;       float* d = (float*)(bb + 16384) + lst * 64 + lch * 8;
;       *(float4*)d = blo; *(float4*)(d + 4) = bhi;
;     }
;     ...
;     for (int s = 0; s < 32; s++) {
;       f32x4 w4n = w4, a4n = a4, b4n = b4;
;       uint2 urn = ur, ukn = uk;
;       float vn = v;
;       if (s < 31) {
;         w4n = *(const f32x4*)(fw + (s + 1) * 64);
;         a4n = *(const f32x4*)(fa + (s + 1) * 64);
;         b4n = *(const f32x4*)(fb + (s + 1) * 64);
;         urn = *(const uint2*)(pr + (s + 1) * 128);
;         ukn = *(const uint2*)(pk + (s + 1) * 128);
;         vn = vb[(s + 1) * 16];
;       }
;       __builtin_amdgcn_sched_barrier(0);
;       const f32x2 klo = {__uint_as_float(uk.x << 16), __uint_as_float(uk.x & 0xFFFF0000u)};
;       const f32x2 khi = {__uint_as_float(uk.y << 16), __uint_as_float(uk.y & 0xFFFF0000u)};
;       const f32x2 rlo = {__uint_as_float(ur.x << 16), __uint_as_float(ur.x & 0xFFFF0000u)};
;       const f32x2 rhi = {__uint_as_float(ur.y << 16), __uint_as_float(ur.y & 0xFFFF0000u)};
;       const f32x2 vv = {v, v};
;       const f32x2 t = Sa * a4.lo + Sb * a4.hi;
;       const f32x2 na = Sa * w4.lo + vv * klo;
;       const f32x2 nb = Sb * w4.hi + vv * khi;
;       float sa = t.x + t.y;
;       float yp = yprev;
;       rowsum16x2(sa, yp);
;       if (s >= 1 && s <= 16) ykeep0 = (jq == s - 1) ? yp : ykeep0;
;       if (s >= 17) ykeep1 = (jq == s - 17) ? yp : ykeep1;
;       const f32x2 sv = {sa, sa};
;       Sa = na + sv * b4.lo;
;       Sb = nb + sv * b4.hi;
;       const f32x2 yy = Sa * rlo + Sb * rhi;
;       yprev = yy.x + yy.y;
;       w4 = w4n; a4 = a4n; b4 = b4n; ur = urn; uk = ukn; v = vn;
;     }
;     {
;       const float yl = rowsum16(yprev);
;       ykeep1 = (jq == 15) ? yl : ykeep1;
;     }
;     if (!dry) { yo[0] = ykeep0; yo[(size_t)16 * 512] = ykeep1; }
;     if (more) sstore((c + 1) & 1);
;     __syncthreads();
	ds_read_b128 v[12:15], v76 offset:29440
	ds_read_b128 v[24:27], v76 offset:41728
	ds_read_b128 v[8:11], v76 offset:25344
	ds_read_b128 v[16:19], v76 offset:33536
	v_pk_mul_f32 v[56:57], v[4:5], v[32:33]
	v_pk_mul_f32 v[64:65], v[4:5], v[20:21]
	v_pk_fma_f32 v[56:57], v[6:7], v[34:35], v[56:57]
	v_pk_fma_f32 v[64:65], v[6:7], v[22:23], v[64:65]
	v_add_f32_e32 v58, v56, v57
	v_pk_mul_f32 v[60:61], v[52:53], v[44:45] op_sel:[1,0] op_sel_hi:[1,1]
	v_pk_mul_f32 v[62:63], v[52:53], v[46:47] op_sel:[1,0] op_sel_hi:[1,1]
	v_add_f32_dpp v58, v58, v58 quad_perm:[1,0,3,2] row_mask:0xf bank_mask:0xf bound_ctrl:1
	v_pk_fma_f32 v[60:61], v[4:5], v[28:29], v[60:61]
	v_add_f32_e32 v66, v64, v65
	v_add_f32_dpp v58, v58, v58 quad_perm:[2,3,0,1] row_mask:0xf bank_mask:0xf bound_ctrl:1
	v_pk_fma_f32 v[62:63], v[6:7], v[30:31], v[62:63]
	v_add_f32_dpp v72, v72, v72 row_half_mirror row_mask:0xf bank_mask:0x5
	v_add_f32_dpp v58, v58, v58 row_half_mirror row_mask:0xf bank_mask:0xf bound_ctrl:1
	s_nop 0
	v_add_f32_dpp v72, v73, v73 row_half_mirror row_mask:0xf bank_mask:0xa
	ds_read_b128 v[20:23], v76 offset:37632
	v_add_f32_dpp v58, v58, v58 row_mirror row_mask:0xf bank_mask:0xf bound_ctrl:1
	v_pk_fma_f32 v[4:5], v[58:59], v[36:37], v[60:61] op_sel_hi:[0,1,1]
	v_pk_fma_f32 v[6:7], v[58:59], v[38:39], v[62:63] op_sel_hi:[0,1,1]
	s_waitcnt lgkmcnt(6)
	v_pk_mul_f32 v[56:57], v[4:5], v[228:229]
	v_pk_mul_f32 v[64:65], v[4:5], v[40:41]
	v_pk_fma_f32 v[56:57], v[6:7], v[230:231], v[56:57]
	v_pk_fma_f32 v[64:65], v[6:7], v[42:43], v[64:65]
	v_add_f32_e32 v58, v56, v57
	v_pk_mul_f32 v[60:61], v[54:55], v[240:241] op_sel_hi:[0,1]
	v_pk_mul_f32 v[62:63], v[54:55], v[242:243] op_sel_hi:[0,1]
	v_add_f32_dpp v58, v58, v58 quad_perm:[1,0,3,2] row_mask:0xf bank_mask:0xf bound_ctrl:1
	v_pk_fma_f32 v[60:61], v[4:5], v[224:225], v[60:61]
	v_add_f32_e32 v67, v64, v65
	v_add_f32_dpp v58, v58, v58 quad_perm:[2,3,0,1] row_mask:0xf bank_mask:0xf bound_ctrl:1
	v_pk_fma_f32 v[62:63], v[6:7], v[226:227], v[62:63]
	v_add_f32_dpp v74, v66, v66 row_mirror row_mask:0xf bank_mask:0x3
	v_add_f32_dpp v58, v58, v58 row_half_mirror row_mask:0xf bank_mask:0xf bound_ctrl:1
	s_nop 0
	v_add_f32_dpp v74, v67, v67 row_mirror row_mask:0xf bank_mask:0xc
	v_add_f32_dpp v58, v58, v58 row_mirror row_mask:0xf bank_mask:0xf bound_ctrl:1
	v_pk_fma_f32 v[4:5], v[58:59], v[232:233], v[60:61] op_sel_hi:[0,1,1]
	v_pk_fma_f32 v[6:7], v[58:59], v[234:235], v[62:63] op_sel_hi:[0,1,1]
	s_waitcnt lgkmcnt(1)
	v_pk_mul_f32 v[56:57], v[4:5], v[12:13]
	v_pk_mul_f32 v[64:65], v[4:5], v[236:237]
	v_pk_fma_f32 v[56:57], v[6:7], v[14:15], v[56:57]
	v_pk_fma_f32 v[64:65], v[6:7], v[238:239], v[64:65]
	v_add_f32_e32 v58, v56, v57
	v_pk_mul_f32 v[60:61], v[54:55], v[24:25] op_sel:[1,0] op_sel_hi:[1,1]
	v_pk_mul_f32 v[62:63], v[54:55], v[26:27] op_sel:[1,0] op_sel_hi:[1,1]
	v_add_f32_dpp v58, v58, v58 quad_perm:[1,0,3,2] row_mask:0xf bank_mask:0xf bound_ctrl:1
	v_pk_fma_f32 v[60:61], v[4:5], v[8:9], v[60:61]
	v_add_f32_e32 v66, v64, v65
	v_add_f32_dpp v58, v58, v58 quad_perm:[2,3,0,1] row_mask:0xf bank_mask:0xf bound_ctrl:1
	v_pk_fma_f32 v[62:63], v[6:7], v[10:11], v[62:63]
	s_nop 0
	v_add_f32_dpp v58, v58, v58 row_half_mirror row_mask:0xf bank_mask:0xf bound_ctrl:1
	s_nop 1
	v_add_f32_dpp v58, v58, v58 row_mirror row_mask:0xf bank_mask:0xf bound_ctrl:1
	v_pk_fma_f32 v[4:5], v[58:59], v[16:17], v[60:61] op_sel_hi:[0,1,1]
	v_pk_fma_f32 v[6:7], v[58:59], v[18:19], v[62:63] op_sel_hi:[0,1,1]
	s_waitcnt lgkmcnt(0)
	v_pk_mul_f32 v[64:65], v[4:5], v[20:21]
	v_pk_fma_f32 v[64:65], v[6:7], v[22:23], v[64:65]
	v_add_f32_e32 v67, v64, v65
	s_cmp_lg_u32 s22, 0
	s_cbranch_scc0 .Lscan_lastB
	s_waitcnt vmcnt(6)
	ds_write_b128 v78, v[84:87] offset:0
	v_lshlrev_b32_e32 v8, 16, v92
	v_and_b32_e32 v9, 0xffff0000, v92
	v_lshlrev_b32_e32 v10, 16, v93
	v_and_b32_e32 v11, 0xffff0000, v93
	ds_write_b128 v78, v[8:11] offset:4096
	v_lshlrev_b32_e32 v12, 16, v94
	v_and_b32_e32 v13, 0xffff0000, v94
	v_lshlrev_b32_e32 v14, 16, v95
	v_and_b32_e32 v15, 0xffff0000, v95
	ds_write_b128 v78, v[12:15] offset:8192
	v_lshlrev_b32_e32 v16, 16, v88
	v_and_b32_e32 v17, 0xffff0000, v88
	v_lshlrev_b32_e32 v18, 16, v89
	v_and_b32_e32 v19, 0xffff0000, v89
	ds_write_b128 v78, v[16:19] offset:12288
	v_lshlrev_b32_e32 v20, 16, v90
	v_and_b32_e32 v21, 0xffff0000, v90
	v_lshlrev_b32_e32 v22, 16, v91
	v_and_b32_e32 v23, 0xffff0000, v91
	ds_write_b128 v78, v[20:23] offset:16384
	v_lshlrev_b32_e32 v24, 16, v96
	ds_write_b32 v79, v24 offset:20480
	s_waitcnt lgkmcnt(0)
	s_barrier
	s_cmp_eq_u32 s28, 0
	s_cbranch_scc1 .LstgbB
	s_nop 5
	s_cmp_eq_u32 s28, 1
	s_cbranch_scc1 .LstgbB
	s_nop 5
	s_cmp_eq_u32 s28, 2
	s_cbranch_scc1 .LstgbB
	s_nop 5
.LstgbB:
	ds_read_b128 v[12:15], v76 offset:4096
	ds_read_b128 v[24:27], v76 offset:16384
	ds_read_b128 v[48:51], v77 offset:20480
	ds_read_b128 v[8:11], v76 offset:0
	ds_read_b128 v[16:19], v76 offset:8192
	ds_read_b128 v[20:23], v76 offset:12288
	ds_read_b128 v[32:35], v76 offset:4352
	ds_read_b128 v[44:47], v76 offset:16640
	ds_read_b128 v[28:31], v76 offset:256
	ds_read_b128 v[36:39], v76 offset:8448
	ds_read_b128 v[40:43], v76 offset:12544
	s_branch .Lscan_tailB

; DI void scan_task(const Params& p, int l, int isP, int b, int h, int rg, char* smem, const bool dry) {
;     ...
;     {
;       const float yl = rowsum16(yprev);
;       ykeep1 = (jq == 15) ? yl : ykeep1;
;     }
;     if (!dry) { yo[0] = ykeep0; yo[(size_t)16 * 512] = ykeep1; }
;     if (more) sstore((c + 1) & 1);
;     __syncthreads();
;   }
;   float* so = isP ? p.out + O_WKVP + ((size_t)((l * 2 + b) * 8 + h) * 64 + i) * 64 + jq * 4
;                   : p.out + O_WKVS + ((size_t)((l * 32 + b) * 8 + h) * 64 + i) * 64 + jq * 4;
;   if (!dry) *(float4*)so = make_float4(Sa.x, Sa.y, Sb.x, Sb.y);
;   __builtin_amdgcn_s_setprio(0);
.Lscan_tailB:
	v_add_f32_dpp v75, v66, v66 row_mirror row_mask:0xf bank_mask:0x3
	v_add_f32_dpp v74, v74, v74 row_half_mirror row_mask:0xf bank_mask:0x5
	v_add_f32_dpp v68, v68, v68 quad_perm:[1,0,3,2] row_mask:0xf bank_mask:0xf
	v_add_f32_dpp v75, v67, v67 row_mirror row_mask:0xf bank_mask:0xc
	v_add_f32_dpp v70, v70, v70 quad_perm:[1,0,3,2] row_mask:0xf bank_mask:0xf
	v_add_f32_dpp v72, v72, v72 quad_perm:[1,0,3,2] row_mask:0xf bank_mask:0xf
	v_add_f32_dpp v74, v75, v75 row_half_mirror row_mask:0xf bank_mask:0xa
	v_add_f32_dpp v68, v68, v68 quad_perm:[2,3,0,1] row_mask:0xf bank_mask:0xf
	v_add_f32_dpp v70, v70, v70 quad_perm:[2,3,0,1] row_mask:0xf bank_mask:0xf
	v_add_f32_dpp v74, v74, v74 quad_perm:[1,0,3,2] row_mask:0xf bank_mask:0xf
	v_add_f32_dpp v72, v72, v72 quad_perm:[2,3,0,1] row_mask:0xf bank_mask:0xf
	v_cndmask_b32_e64 v68, v68, v70, s[18:19]
	v_add_f32_dpp v74, v74, v74 quad_perm:[2,3,0,1] row_mask:0xf bank_mask:0xf
	v_cndmask_b32_e64 v72, v72, v74, s[18:19]
	v_cndmask_b32_e64 v68, v68, v72, s[20:21]
	global_store_dword v83, v68, s[14:15]
	s_add_u32 s14, s14, 0x8000
	s_addc_u32 s15, s15, 0
	s_add_i32 s16, s16, 2
	s_cmp_lt_u32 s16, s17
	s_cbranch_scc1 .Lscan_loop
	s_waitcnt vmcnt(0)
	global_store_dwordx4 v59, v[4:7], s[24:25]
	s_cmp_gt_i32 s93, 63
	s_cbranch_scc1 .Lscan_nosig
	s_load_dwordx2 s[8:9], s[0:1], 0x1b0
	s_lshl_b32 s12, s93, 2
	s_addk_i32 s12, 0x3000
	v_mov_b32_e32 v8, s12
	v_mov_b32_e32 v9, 1
	v_cmp_eq_u32_e32 vcc, 0, v182
	s_and_saveexec_b64 s[12:13], vcc
	s_waitcnt lgkmcnt(0)
	global_atomic_add v8, v9, s[8:9]
	s_or_b64 exec, exec, s[12:13]
.Lscan_nosig:
	v_readlane_b32 s10, v254, 51
	v_readlane_b32 s11, v254, 52
	s_setprio 0
	v_readlane_b32 s26, v254, 59
	v_readlane_b32 s27, v254, 60
